# P3c: first two phase waits of a unit use vmcnt(24) after the first unit so they do not wait for the previous unit's 16 epilogue stores
# baseline (speedup 1.0000x reference)
; #define G8_STAGE(bufoff, gbase, NM) do { _Pragma("unroll") for (int _i = 0; _i < 2; ++_i) { \
;     const char* _b = (const char*)(gbase) + (_i ? p2##NM : (size_t)0); asm volatile("" : "+s"(_b));     \
;     __builtin_amdgcn_global_load_lds((const unsigned*)(_b + voff##NM), (LAS unsigned*)(lds + (bufoff) + ldsw + _i * 8192), 16, 0, 0); } } while (0)
; #define G8_WAIT_V(n) asm volatile("s_waitcnt vmcnt(" #n ")" ::: "memory")
; #define G8_BAR __builtin_amdgcn_s_barrier()
;     ...
;   G8_STAGE(G8_SB(0, 0), cB, B); G8_STAGE(G8_SB(0, 1), cB + hstepB, B); G8_STAGE(G8_SA(0, 0), cA, A); G8_STAGE(G8_SA(0, 1), cA + hstepA, A);
;   if (wr == 1) G8_BAR;
;   G8_WAIT_V(2); G8_BAR;
;   G8_STAGE(G8_SB(1, 0), cB + kstep, B); G8_STAGE(G8_SA(1, 0), cA + kstep, A); G8_STAGE(G8_SB(1, 1), cB + hstepB + kstep, B);
;   G8_WAIT_V(6); G8_BAR;
;   for (;;) {
.LBB0_952:
	s_lshl_b32 s13, s13, 13
	s_ashr_i32 s34, s16, 1
	s_lshl_b32 s14, s14, 13
	s_and_b32 s13, s13, 0x6000
	s_add_u32 s16, s4, 0x80
	s_addc_u32 s17, s5, 0
	s_waitcnt vmcnt(2)
	s_barrier
	s_add_i32 s47, s0, 0x18000
	s_mov_b32 m0, s47
	v_lshl_add_u64 v[2:3], s[16:17], 0, v[198:199]
	s_add_u32 s16, s4, 0x4080
	s_addc_u32 s17, s5, 0
	global_load_lds_dwordx4 v[2:3], off
	s_add_i32 s48, s0, 0x1a000
	v_lshl_add_u64 v[2:3], s[16:17], 0, v[198:199]
	s_add_u32 s16, s8, 0x80
	s_mov_b32 m0, s48
	s_addc_u32 s17, s9, 0
	global_load_lds_dwordx4 v[2:3], off
	s_add_i32 s49, s0, 0x8000
	v_lshl_add_u64 v[2:3], s[16:17], 0, v[196:197]
	s_add_u32 s16, s8, 0x40080
	s_mov_b32 m0, s49
	s_addc_u32 s17, s9, 0
	global_load_lds_dwordx4 v[2:3], off
	s_add_i32 s50, s0, 0xa000
	v_lshl_add_u64 v[2:3], s[16:17], 0, v[196:197]
	s_add_u32 s16, s4, 0x8080
	s_mov_b32 m0, s50
	s_addc_u32 s17, s5, 0
	global_load_lds_dwordx4 v[2:3], off
	s_add_i32 s51, s0, 0x1c000
	s_mov_b32 m0, s51
	v_lshl_add_u64 v[2:3], s[16:17], 0, v[198:199]
	s_add_u32 s16, s4, 0xc080
	s_addc_u32 s17, s5, 0
	s_add_i32 s52, s0, 0x1e000
	global_load_lds_dwordx4 v[2:3], off
	s_mov_b32 m0, s52
	v_lshl_add_u64 v[2:3], s[16:17], 0, v[198:199]
	global_load_lds_dwordx4 v[2:3], off
	v_and_b32_e32 v1, 15, v0
	v_and_b32_e32 v2, 48, v0
	v_lshlrev_b32_e32 v0, 2, v0
	v_lshlrev_b32_e32 v1, 6, v1
	v_and_b32_e32 v0, 32, v0
	v_or_b32_e32 v3, v1, v2
	v_bitop3_b32 v1, v1, v0, v2 bitop3:0x36
	v_or_b32_e32 v1, s13, v1
	s_waitcnt vmcnt(6)
	v_bitop3_b32 v0, v3, s14, v0 bitop3:0xde
	s_cmpk_lt_u32 s12, 0x100
	v_add_u32_e32 v201, 0, v1
	s_cselect_b64 s[12:13], -1, 0
	s_add_i32 s53, s88, s89
	v_add_u32_e32 v202, 0x10000, v201
	v_add_u32_e32 v203, 0x1000, v202
	v_add_u32_e32 v204, 0, v0
	s_mov_b32 s14, 0x41800000
	s_mov_b64 s[16:17], 0x100000
	s_mov_b32 s64, 0
	s_mov_b32 s54, 0x100000
	s_mov_b64 s[18:19], 0x120000
	s_mov_b32 s55, 0x120000
	s_mov_b64 s[20:21], 0x140000
	s_mov_b32 s56, 0x140000
	s_mov_b64 s[22:23], 0x160000
	s_mov_b32 s57, 0x160000
	s_mov_b64 s[28:29], s[8:9]
	s_barrier
	s_branch .LBB0_955

; #define G8_STAGE(bufoff, gbase, NM) do { _Pragma("unroll") for (int _i = 0; _i < 2; ++_i) { \
;     const char* _b = (const char*)(gbase) + (_i ? p2##NM : (size_t)0); asm volatile("" : "+s"(_b));     \
;     __builtin_amdgcn_global_load_lds((const unsigned*)(_b + voff##NM), (LAS unsigned*)(lds + (bufoff) + ldsw + _i * 8192), 16, 0, 0); } } while (0)
; #define G8_WAIT_V(n) asm volatile("s_waitcnt vmcnt(" #n ")" ::: "memory")
; #define G8_WAIT_L(n) asm volatile("s_waitcnt lgkmcnt(" #n ")" ::: "memory")
; #define G8_BAR __builtin_amdgcn_s_barrier()
; #define G8_SCHED __builtin_amdgcn_sched_barrier(0)
;     ...
;       G8_LDB(B0, 0, 0); G8_LDB(B1, 0, 1); G8_SCHED; G8_LDA(At, 0, 0); G8_STAGE(G8_SA(1, 1), a1, A);
;       const bool d0a = (BD == 0) || (BD == 1 && t < (nt >> 1)) || (BD == 2 && !(cur.pn & 1));
;       const bool d1a = (BD == 0) || (BD == 1 && t >= (nt >> 1)) || (BD == 2 && !(cur.pn & 1));
;       const bool d0b = (BD == 0) || (BD == 1 && t < (nt >> 1)) || (BD == 2 && (cur.pn & 1));
;       const bool d1b = (BD == 0) || (BD == 1 && t >= (nt >> 1)) || (BD == 2 && (cur.pn & 1));
;       G8_WAIT_V(8); G8_WAIT_L(0); G8_BAR; if (d0a) G8_MMA(0, 0, At, B0); if (d1a) G8_MMA(0, 1, At, B1); G8_BAR; G8_SCHED;
.LBB0_961:
	s_add_u32 s60, s8, 0x80080
	s_addc_u32 s61, s9, 0
	s_add_u32 s36, s28, 0x80
	s_addc_u32 s37, s29, 0
	s_add_u32 s38, s4, 0x80
	s_addc_u32 s39, s5, 0
	s_mov_b64 s[42:43], s[4:5]
	s_mov_b64 s[8:9], s[28:29]
	ds_read_b128 v[0:3], v202
	ds_read_b128 v[4:7], v202 offset:1024
	ds_read_b128 v[8:11], v202 offset:2048
	ds_read_b128 v[12:15], v202 offset:3072
	ds_read_b128 v[16:19], v203
	ds_read_b128 v[20:23], v203 offset:1024
	ds_read_b128 v[24:27], v203 offset:2048
	ds_read_b128 v[28:31], v203 offset:3072
	s_and_b32 s27, s34, 1
	s_cmp_eq_u32 s27, 0
	s_cselect_b64 s[44:45], -1, 0
	s_cmp_eq_u32 s27, 1
	s_cselect_b64 s[40:41], -1, 0
	s_add_i32 m0, s0, 0xc000
	s_mov_b64 s[62:63], s[60:61]
	s_add_u32 s60, s60, 0x40000
	s_waitcnt lgkmcnt(0)
	ds_read_b128 v[32:35], v204
	ds_read_b128 v[36:39], v204 offset:1024
	ds_read_b128 v[40:43], v204 offset:2048
	ds_read_b128 v[44:47], v204 offset:3072
	ds_read_b128 v[48:51], v204 offset:4096
	ds_read_b128 v[52:55], v204 offset:5120
	ds_read_b128 v[56:59], v204 offset:6144
	ds_read_b128 v[60:63], v204 offset:7168
	s_addc_u32 s61, s61, 0
	v_lshl_add_u64 v[66:67], s[62:63], 0, v[196:197]
	global_load_lds_dwordx4 v[66:67], off
	s_add_i32 m0, s0, 0xe000
	v_lshl_add_u64 v[66:67], s[60:61], 0, v[196:197]
	global_load_lds_dwordx4 v[66:67], off
	s_cmp_eq_u32 s64, 0
	s_cbranch_scc1 .Lq3_wa0
	s_waitcnt vmcnt(24)
	s_branch .Lq3_wa1

; #define G8_STAGE(bufoff, gbase, NM) do { _Pragma("unroll") for (int _i = 0; _i < 2; ++_i) { \
;     const char* _b = (const char*)(gbase) + (_i ? p2##NM : (size_t)0); asm volatile("" : "+s"(_b));     \
;     __builtin_amdgcn_global_load_lds((const unsigned*)(_b + voff##NM), (LAS unsigned*)(lds + (bufoff) + ldsw + _i * 8192), 16, 0, 0); } } while (0)
; #define G8_WAIT_V(n) asm volatile("s_waitcnt vmcnt(" #n ")" ::: "memory")
; #define G8_WAIT_L(n) asm volatile("s_waitcnt lgkmcnt(" #n ")" ::: "memory")
; #define G8_BAR __builtin_amdgcn_s_barrier()
; #define G8_SCHED __builtin_amdgcn_sched_barrier(0)
;     ...
;       G8_WAIT_V(8); G8_WAIT_L(0); G8_BAR; if (d0a) G8_MMA(0, 0, At, B0); if (d1a) G8_MMA(0, 1, At, B1); G8_BAR; G8_SCHED;
;       G8_LDA(At, 0, 1); G8_STAGE(G8_SB(0, 0), b2, B); G8_STAGE(G8_SB(0, 1), b2 + hstepB, B); G8_STAGE(G8_SA(0, 0), a2, A);
;       G8_WAIT_V(8); G8_WAIT_L(0); G8_BAR; if (d0a) G8_MMA(1, 0, At, B0); if (d1a) G8_MMA(1, 1, At, B1); G8_BAR; G8_SCHED;
.Lq3_wa1:
	s_waitcnt lgkmcnt(0)
	v_mov_b32_e32 v66, v65
	v_mov_b32_e32 v67, v65
	v_mov_b32_e32 v64, v65
	v_mov_b64_e32 v[86:87], v[66:67]
	v_mov_b64_e32 v[90:91], v[66:67]
	v_mov_b64_e32 v[118:119], v[66:67]
	v_mov_b64_e32 v[122:123], v[66:67]
	v_mov_b64_e32 v[150:151], v[66:67]
	v_mov_b64_e32 v[154:155], v[66:67]
	v_mov_b64_e32 v[182:183], v[66:67]
	v_mov_b64_e32 v[186:187], v[66:67]
	v_mov_b64_e32 v[94:95], v[66:67]
	v_mov_b64_e32 v[98:99], v[66:67]
	v_mov_b64_e32 v[126:127], v[66:67]
	v_mov_b64_e32 v[130:131], v[66:67]
	v_mov_b64_e32 v[158:159], v[66:67]
	v_mov_b64_e32 v[162:163], v[66:67]
	v_mov_b64_e32 v[190:191], v[66:67]
	v_mov_b64_e32 v[194:195], v[66:67]
	s_and_b64 vcc, exec, s[40:41]
	v_mov_b64_e32 v[84:85], v[64:65]
	v_mov_b64_e32 v[88:89], v[64:65]
	v_mov_b64_e32 v[116:117], v[64:65]
	v_mov_b64_e32 v[120:121], v[64:65]
	v_mov_b64_e32 v[148:149], v[64:65]
	v_mov_b64_e32 v[152:153], v[64:65]
	v_mov_b64_e32 v[180:181], v[64:65]
	v_mov_b64_e32 v[184:185], v[64:65]
	v_mov_b64_e32 v[92:93], v[64:65]
	v_mov_b64_e32 v[96:97], v[64:65]
	v_mov_b64_e32 v[124:125], v[64:65]
	v_mov_b64_e32 v[128:129], v[64:65]
	v_mov_b64_e32 v[156:157], v[64:65]
	v_mov_b64_e32 v[160:161], v[64:65]
	v_mov_b64_e32 v[188:189], v[64:65]
	v_mov_b64_e32 v[192:193], v[64:65]
	s_barrier
	s_cbranch_vccnz .LBB0_963
	s_setprio 1
	s_waitcnt lgkmcnt(0)
	v_mfma_f32_16x16x128_f8f6f4 v[192:195], v[0:7], v[32:39], 0
	v_mfma_f32_16x16x128_f8f6f4 v[188:191], v[8:15], v[32:39], 0
	v_mfma_f32_16x16x128_f8f6f4 v[160:163], v[0:7], v[40:47], 0
	v_mfma_f32_16x16x128_f8f6f4 v[156:159], v[8:15], v[40:47], 0
	v_mfma_f32_16x16x128_f8f6f4 v[128:131], v[0:7], v[48:55], 0
	v_mfma_f32_16x16x128_f8f6f4 v[124:127], v[8:15], v[48:55], 0
	v_mfma_f32_16x16x128_f8f6f4 v[96:99], v[0:7], v[56:63], 0
	v_mfma_f32_16x16x128_f8f6f4 v[92:95], v[8:15], v[56:63], 0
	s_setprio 0
	s_setprio 1
	v_mfma_f32_16x16x128_f8f6f4 v[184:187], v[16:23], v[32:39], 0
	v_mfma_f32_16x16x128_f8f6f4 v[180:183], v[24:31], v[32:39], 0
	v_mfma_f32_16x16x128_f8f6f4 v[152:155], v[16:23], v[40:47], 0
	v_mfma_f32_16x16x128_f8f6f4 v[148:151], v[24:31], v[40:47], 0
	v_mfma_f32_16x16x128_f8f6f4 v[120:123], v[16:23], v[48:55], 0
	v_mfma_f32_16x16x128_f8f6f4 v[116:119], v[24:31], v[48:55], 0
	v_mfma_f32_16x16x128_f8f6f4 v[88:91], v[16:23], v[56:63], 0
	v_mfma_f32_16x16x128_f8f6f4 v[84:87], v[24:31], v[56:63], 0
	s_setprio 0
.LBB0_963:
	s_barrier
	s_mov_b64 s[60:61], s[42:43]
	s_waitcnt lgkmcnt(0)
	ds_read_b128 v[32:35], v204 offset:16384
	ds_read_b128 v[36:39], v204 offset:17408
	ds_read_b128 v[40:43], v204 offset:18432
	ds_read_b128 v[44:47], v204 offset:19456
	ds_read_b128 v[48:51], v204 offset:20480
	ds_read_b128 v[52:55], v204 offset:21504
	ds_read_b128 v[56:59], v204 offset:22528
	ds_read_b128 v[60:63], v204 offset:23552
	s_mov_b32 m0, s1
	v_lshl_add_u64 v[66:67], s[60:61], 0, v[198:199]
	s_add_u32 s60, s42, 0x4000
	s_addc_u32 s61, s43, 0
	global_load_lds_dwordx4 v[66:67], off
	s_mov_b32 m0, s2
	v_lshl_add_u64 v[66:67], s[60:61], 0, v[198:199]
	s_add_u32 s60, s42, 0x8000
	s_addc_u32 s61, s43, 0
	s_add_u32 s42, s42, 0xc000
	global_load_lds_dwordx4 v[66:67], off
	s_mov_b32 m0, s3
	v_lshl_add_u64 v[66:67], s[60:61], 0, v[198:199]
	s_addc_u32 s43, s43, 0
	global_load_lds_dwordx4 v[66:67], off
	s_mov_b32 m0, s15
	v_lshl_add_u64 v[66:67], s[42:43], 0, v[198:199]
	s_mov_b64 s[42:43], s[8:9]
	global_load_lds_dwordx4 v[66:67], off
	s_mov_b32 m0, s0
	v_lshl_add_u64 v[66:67], s[42:43], 0, v[196:197]
	s_add_u32 s42, s8, 0x40000
	s_addc_u32 s43, s9, 0
	global_load_lds_dwordx4 v[66:67], off
	s_mov_b32 m0, s31
	v_lshl_add_u64 v[66:67], s[42:43], 0, v[196:197]
	global_load_lds_dwordx4 v[66:67], off
	s_cmp_eq_u32 s64, 0
	s_cbranch_scc1 .Lq3_wb0
	s_waitcnt vmcnt(24)
	s_branch .Lq3_wb1

; #define G8_STAGE(bufoff, gbase, NM) do { _Pragma("unroll") for (int _i = 0; _i < 2; ++_i) { \
;     const char* _b = (const char*)(gbase) + (_i ? p2##NM : (size_t)0); asm volatile("" : "+s"(_b));     \
;     __builtin_amdgcn_global_load_lds((const unsigned*)(_b + voff##NM), (LAS unsigned*)(lds + (bufoff) + ldsw + _i * 8192), 16, 0, 0); } } while (0)
; #define G8_WAIT_V(n) asm volatile("s_waitcnt vmcnt(" #n ")" ::: "memory")
; #define G8_WAIT_L(n) asm volatile("s_waitcnt lgkmcnt(" #n ")" ::: "memory")
; #define G8_BAR __builtin_amdgcn_s_barrier()
; #define G8_SCHED __builtin_amdgcn_sched_barrier(0)
;     ...
;       G8_WAIT_V(8); G8_WAIT_L(0); G8_BAR; if (d0a) G8_MMA(0, 0, At, B0); if (d1a) G8_MMA(0, 1, At, B1); G8_BAR; G8_SCHED;
;       G8_LDA(At, 0, 1); G8_STAGE(G8_SB(0, 0), b2, B); G8_STAGE(G8_SB(0, 1), b2 + hstepB, B); G8_STAGE(G8_SA(0, 0), a2, A);
;       G8_WAIT_V(8); G8_WAIT_L(0); G8_BAR; if (d0a) G8_MMA(1, 0, At, B0); if (d1a) G8_MMA(1, 1, At, B1); G8_BAR; G8_SCHED;
.Lq3_wb1:
	s_waitcnt lgkmcnt(0)
	s_andn2_b64 vcc, exec, s[44:45]
	s_barrier
	s_cbranch_vccnz .LBB0_965
	s_setprio 1
	s_waitcnt lgkmcnt(0)
	v_mfma_f32_16x16x128_f8f6f4 v[176:179], v[0:7], v[32:39], 0
	v_mfma_f32_16x16x128_f8f6f4 v[172:175], v[8:15], v[32:39], 0
	v_mfma_f32_16x16x128_f8f6f4 v[144:147], v[0:7], v[40:47], 0
	v_mfma_f32_16x16x128_f8f6f4 v[140:143], v[8:15], v[40:47], 0
	v_mfma_f32_16x16x128_f8f6f4 v[112:115], v[0:7], v[48:55], 0
	v_mfma_f32_16x16x128_f8f6f4 v[108:111], v[8:15], v[48:55], 0
	v_mfma_f32_16x16x128_f8f6f4 v[80:83], v[0:7], v[56:63], 0
	v_mfma_f32_16x16x128_f8f6f4 v[76:79], v[8:15], v[56:63], 0
	s_setprio 0
	s_setprio 1
	v_mfma_f32_16x16x128_f8f6f4 v[168:171], v[16:23], v[32:39], 0
	v_mfma_f32_16x16x128_f8f6f4 v[164:167], v[24:31], v[32:39], 0
	v_mfma_f32_16x16x128_f8f6f4 v[136:139], v[16:23], v[40:47], 0
	v_mfma_f32_16x16x128_f8f6f4 v[132:135], v[24:31], v[40:47], 0
	v_mfma_f32_16x16x128_f8f6f4 v[104:107], v[16:23], v[48:55], 0
	v_mfma_f32_16x16x128_f8f6f4 v[100:103], v[24:31], v[48:55], 0
	v_mfma_f32_16x16x128_f8f6f4 v[72:75], v[16:23], v[56:63], 0
	v_mfma_f32_16x16x128_f8f6f4 v[68:71], v[24:31], v[56:63], 0
	s_setprio 0
	s_branch .LBB0_966

;   __device__ __forceinline__ void operator()(const Acc& acc, const GUnit& u, int wr, int wc, int fr, int fq) const {
;     const int row0 = u.pm * 256 + wr * 64 + fr;
;     unsigned char* ob = Q0 + (size_t)u.pn * 256 + wc * 32 + 8 * fq;
; #pragma unroll
;     for (int ai = 0; ai < 2; ++ai)
; #pragma unroll
;       for (int m = 0; m < 4; ++m) {
;         const int row = row0 + ai * 128 + m * 16;
; #pragma unroll
;         for (int bj = 0; bj < 2; ++bj) { const f32x4 a = acc[ai][bj][m][0] * osc, b = acc[ai][bj][m][1] * osc; u32x2 w;
;           w[0] = __builtin_amdgcn_cvt_pk_fp8_f32(a[0], a[1], 0, false); w[0] = __builtin_amdgcn_cvt_pk_fp8_f32(a[2], a[3], w[0], true);
;           w[1] = __builtin_amdgcn_cvt_pk_fp8_f32(b[0], b[1], 0, false); w[1] = __builtin_amdgcn_cvt_pk_fp8_f32(b[2], b[3], w[1], true);
;           *(u32x2*)(ob + (size_t)row * 8192 + bj * 128) = w; }
;       }
;   }
.LBB0_972:
	v_mov_b32_e32 v0, v200
	s_lshl_b32 s8, s30, 8
	v_readfirstlane_b32 s27, v0
	s_ashr_i32 s9, s27, 2
	s_andn2_b32 s9, s9, 63
	s_add_i32 s9, s9, s8
	v_and_or_b32 v2, v0, 15, s9
	v_lshrrev_b32_e32 v0, 1, v0
	v_and_b32_e32 v64, 24, v0
	v_and_b32_e32 v210, 8, v200
	v_mov_b32_e32 v212, 0x10000
	v_lshl_or_b32 v64, v210, 2, v64
	v_xor_b32_e32 v210, 8, v210
	v_mov_b32_e32 v213, 0
	v_lshl_or_b32 v64, v210, 13, v64
	v_mov_b32_e32 v8, v65
	v_mov_b32_e32 v9, v65
	v_cvt_scalef32_pk_fp8_f32 v8, v192, v193, s14
	v_cvt_scalef32_pk_fp8_f32 v9, v188, v189, s14
	s_ashr_i32 s35, s34, 31
	s_lshl_b64 s[8:9], s[34:35], 8
	v_cvt_scalef32_pk_fp8_f32 v8, v194, v195, s14 op_sel:[0,0,0,1]
	v_cvt_scalef32_pk_fp8_f32 v9, v190, v191, s14 op_sel:[0,0,0,1]
	v_mov_b32_e32 v10, v65
	v_mov_b32_e32 v11, v65
	s_add_u32 s8, s92, s8
	v_cvt_scalef32_pk_fp8_f32 v10, v184, v185, s14
	v_cvt_scalef32_pk_fp8_f32 v11, v180, v181, s14
	s_addc_u32 s9, s93, s9
	s_and_b32 s27, s27, 0xc0
	s_add_u32 s8, s8, s27
	s_addc_u32 s9, s9, 0
	s_sub_u32 s8, s8, 0x10000
	s_subb_u32 s9, s9, 0
	v_ashrrev_i32_e32 v3, 31, v2
	v_cvt_scalef32_pk_fp8_f32 v10, v186, v187, s14 op_sel:[0,0,0,1]
	v_cvt_scalef32_pk_fp8_f32 v11, v182, v183, s14 op_sel:[0,0,0,1]
	v_lshl_add_u64 v[4:5], s[8:9], 0, v[64:65]
	v_lshlrev_b64 v[0:1], 13, v[2:3]
	v_lshl_add_u64 v[0:1], v[4:5], 0, v[0:1]
	v_mov_b32_e32 v214, v8
	v_mov_b32_e32 v215, v9
	v_mov_b32_dpp v8, v10 row_ror:8 row_mask:0xf bank_mask:0xc
	v_mov_b32_dpp v9, v11 row_ror:8 row_mask:0xf bank_mask:0xc
	v_mov_b32_dpp v10, v214 row_ror:8 row_mask:0xf bank_mask:0x3
	v_mov_b32_dpp v11, v215 row_ror:8 row_mask:0xf bank_mask:0x3
	v_lshl_add_u64 v[216:217], v[0:1], 0, v[212:213]
	global_store_dwordx2 v[0:1], v[8:9], off
	global_store_dwordx2 v[216:217], v[10:11], off
	v_mov_b32_e32 v12, v65
	v_mov_b32_e32 v13, v65
	v_cvt_scalef32_pk_fp8_f32 v12, v160, v161, s14
	v_cvt_scalef32_pk_fp8_f32 v13, v156, v157, s14
	v_cvt_scalef32_pk_fp8_f32 v12, v162, v163, s14 op_sel:[0,0,0,1]
	v_cvt_scalef32_pk_fp8_f32 v13, v158, v159, s14 op_sel:[0,0,0,1]
	v_mov_b32_e32 v14, v65
	v_mov_b32_e32 v15, v65
	v_cvt_scalef32_pk_fp8_f32 v14, v152, v153, s14
	v_cvt_scalef32_pk_fp8_f32 v15, v148, v149, s14
	v_or_b32_e32 v6, 16, v2
	v_ashrrev_i32_e32 v7, 31, v6
	v_cvt_scalef32_pk_fp8_f32 v14, v154, v155, s14 op_sel:[0,0,0,1]
	v_cvt_scalef32_pk_fp8_f32 v15, v150, v151, s14 op_sel:[0,0,0,1]
	v_lshlrev_b64 v[6:7], 13, v[6:7]
	v_lshl_add_u64 v[6:7], v[4:5], 0, v[6:7]
	v_mov_b32_e32 v214, v12
	v_mov_b32_e32 v215, v13
	v_mov_b32_dpp v12, v14 row_ror:8 row_mask:0xf bank_mask:0xc
	v_mov_b32_dpp v13, v15 row_ror:8 row_mask:0xf bank_mask:0xc
	v_mov_b32_dpp v14, v214 row_ror:8 row_mask:0xf bank_mask:0x3
	v_mov_b32_dpp v15, v215 row_ror:8 row_mask:0xf bank_mask:0x3
	v_lshl_add_u64 v[216:217], v[6:7], 0, v[212:213]
	global_store_dwordx2 v[6:7], v[12:13], off
	global_store_dwordx2 v[216:217], v[14:15], off
	v_mov_b32_e32 v12, v65
	v_mov_b32_e32 v13, v65
	v_cvt_scalef32_pk_fp8_f32 v12, v128, v129, s14
	v_cvt_scalef32_pk_fp8_f32 v13, v124, v125, s14
	v_cvt_scalef32_pk_fp8_f32 v12, v130, v131, s14 op_sel:[0,0,0,1]
	v_cvt_scalef32_pk_fp8_f32 v13, v126, v127, s14 op_sel:[0,0,0,1]
	v_mov_b32_e32 v14, v65
	v_mov_b32_e32 v15, v65
	v_cvt_scalef32_pk_fp8_f32 v14, v120, v121, s14
	v_cvt_scalef32_pk_fp8_f32 v15, v116, v117, s14
	v_or_b32_e32 v6, 32, v2
	v_ashrrev_i32_e32 v7, 31, v6
	v_cvt_scalef32_pk_fp8_f32 v14, v122, v123, s14 op_sel:[0,0,0,1]
	v_cvt_scalef32_pk_fp8_f32 v15, v118, v119, s14 op_sel:[0,0,0,1]
	v_lshlrev_b64 v[6:7], 13, v[6:7]
	v_lshl_add_u64 v[6:7], v[4:5], 0, v[6:7]
	v_mov_b32_e32 v214, v12
	v_mov_b32_e32 v215, v13
	v_mov_b32_dpp v12, v14 row_ror:8 row_mask:0xf bank_mask:0xc
	v_mov_b32_dpp v13, v15 row_ror:8 row_mask:0xf bank_mask:0xc
	v_mov_b32_dpp v14, v214 row_ror:8 row_mask:0xf bank_mask:0x3
	v_mov_b32_dpp v15, v215 row_ror:8 row_mask:0xf bank_mask:0x3
	v_lshl_add_u64 v[216:217], v[6:7], 0, v[212:213]
	global_store_dwordx2 v[6:7], v[12:13], off
	global_store_dwordx2 v[216:217], v[14:15], off
	v_mov_b32_e32 v10, v65
	v_mov_b32_e32 v11, v65
	v_cvt_scalef32_pk_fp8_f32 v10, v96, v97, s14
	v_cvt_scalef32_pk_fp8_f32 v11, v92, v93, s14
	v_cvt_scalef32_pk_fp8_f32 v10, v98, v99, s14 op_sel:[0,0,0,1]
	v_cvt_scalef32_pk_fp8_f32 v11, v94, v95, s14 op_sel:[0,0,0,1]
	v_mov_b32_e32 v12, v65
	v_mov_b32_e32 v13, v65
	v_cvt_scalef32_pk_fp8_f32 v12, v88, v89, s14
	v_cvt_scalef32_pk_fp8_f32 v13, v84, v85, s14
	v_or_b32_e32 v2, 48, v2
	v_ashrrev_i32_e32 v3, 31, v2
	v_lshlrev_b64 v[2:3], 13, v[2:3]
	v_cvt_scalef32_pk_fp8_f32 v12, v90, v91, s14 op_sel:[0,0,0,1]
	v_cvt_scalef32_pk_fp8_f32 v13, v86, v87, s14 op_sel:[0,0,0,1]
	v_lshl_add_u64 v[2:3], v[4:5], 0, v[2:3]
	v_mov_b32_e32 v8, v65
	v_mov_b32_e32 v9, v65
	v_cvt_scalef32_pk_fp8_f32 v8, v176, v177, s14
	v_cvt_scalef32_pk_fp8_f32 v9, v172, v173, s14
	v_mov_b32_e32 v214, v10
; #define G8_BAR __builtin_amdgcn_s_barrier()
;     ...
;     if (!has_next) break;
; #pragma unroll
;     for (int a = 0; a < 2; ++a)
; #pragma unroll
;       for (int b = 0; b < 2; ++b)
; #pragma unroll
;         for (int m = 0; m < 4; ++m)
; #pragma unroll
;           for (int n = 0; n < 2; ++n) acc[a][b][m][n] = (f32x4){0.f, 0.f, 0.f, 0.f};
;     cur = nxt; cA = nA; cB = nB; ++ui;
;     if (wr == 1) G8_BAR;
;   __device__ __forceinline__ void operator()(const Acc& acc, const GUnit& u, int wr, int wc, int fr, int fq) const {
;     const int row0 = u.pm * 256 + wr * 64 + fr;
;     unsigned char* ob = Q0 + (size_t)u.pn * 256 + wc * 32 + 8 * fq;
; #pragma unroll
;     for (int ai = 0; ai < 2; ++ai)
; #pragma unroll
;       for (int m = 0; m < 4; ++m) {
;         const int row = row0 + ai * 128 + m * 16;
; #pragma unroll
;         for (int bj = 0; bj < 2; ++bj) { const f32x4 a = acc[ai][bj][m][0] * osc, b = acc[ai][bj][m][1] * osc; u32x2 w;
;           w[0] = __builtin_amdgcn_cvt_pk_fp8_f32(a[0], a[1], 0, false); w[0] = __builtin_amdgcn_cvt_pk_fp8_f32(a[2], a[3], w[0], true);
;           w[1] = __builtin_amdgcn_cvt_pk_fp8_f32(b[0], b[1], 0, false); w[1] = __builtin_amdgcn_cvt_pk_fp8_f32(b[2], b[3], w[1], true);
;           *(u32x2*)(ob + (size_t)row * 8192 + bj * 128) = w; }
;       }
;   }
	v_mov_b32_e32 v215, v11
	v_mov_b32_dpp v10, v12 row_ror:8 row_mask:0xf bank_mask:0xc
	v_mov_b32_dpp v11, v13 row_ror:8 row_mask:0xf bank_mask:0xc
	v_mov_b32_dpp v12, v214 row_ror:8 row_mask:0xf bank_mask:0x3
	v_mov_b32_dpp v13, v215 row_ror:8 row_mask:0xf bank_mask:0x3
	v_lshl_add_u64 v[216:217], v[2:3], 0, v[212:213]
	global_store_dwordx2 v[2:3], v[10:11], off
	global_store_dwordx2 v[216:217], v[12:13], off
	v_cvt_scalef32_pk_fp8_f32 v8, v178, v179, s14 op_sel:[0,0,0,1]
	v_cvt_scalef32_pk_fp8_f32 v9, v174, v175, s14 op_sel:[0,0,0,1]
	v_mov_b32_e32 v10, v65
	v_mov_b32_e32 v11, v65
	v_cvt_scalef32_pk_fp8_f32 v10, v168, v169, s14
	v_cvt_scalef32_pk_fp8_f32 v11, v164, v165, s14
	v_cvt_scalef32_pk_fp8_f32 v10, v170, v171, s14 op_sel:[0,0,0,1]
	v_cvt_scalef32_pk_fp8_f32 v11, v166, v167, s14 op_sel:[0,0,0,1]
	v_add_co_u32_e32 v4, vcc, s54, v0
	v_lshl_add_u64 v[2:3], v[0:1], 0, s[16:17]
	s_nop 0
	v_addc_co_u32_e32 v5, vcc, 0, v1, vcc
	v_mov_b32_e32 v214, v8
	v_mov_b32_e32 v215, v9
	v_mov_b32_dpp v8, v10 row_ror:8 row_mask:0xf bank_mask:0xc
	v_mov_b32_dpp v9, v11 row_ror:8 row_mask:0xf bank_mask:0xc
	v_mov_b32_dpp v10, v214 row_ror:8 row_mask:0xf bank_mask:0x3
	v_mov_b32_dpp v11, v215 row_ror:8 row_mask:0xf bank_mask:0x3
	v_lshl_add_u64 v[216:217], v[4:5], 0, v[212:213]
	global_store_dwordx2 v[4:5], v[8:9], off
	global_store_dwordx2 v[216:217], v[10:11], off
	v_mov_b32_e32 v8, v65
	v_mov_b32_e32 v9, v65
	v_cvt_scalef32_pk_fp8_f32 v8, v144, v145, s14
	v_cvt_scalef32_pk_fp8_f32 v9, v140, v141, s14
	v_cvt_scalef32_pk_fp8_f32 v8, v146, v147, s14 op_sel:[0,0,0,1]
	v_cvt_scalef32_pk_fp8_f32 v9, v142, v143, s14 op_sel:[0,0,0,1]
	v_mov_b32_e32 v10, v65
	v_mov_b32_e32 v11, v65
	v_cvt_scalef32_pk_fp8_f32 v10, v136, v137, s14
	v_cvt_scalef32_pk_fp8_f32 v11, v132, v133, s14
	v_cvt_scalef32_pk_fp8_f32 v10, v138, v139, s14 op_sel:[0,0,0,1]
	v_cvt_scalef32_pk_fp8_f32 v11, v134, v135, s14 op_sel:[0,0,0,1]
	v_add_co_u32_e32 v4, vcc, s55, v0
	v_lshl_add_u64 v[2:3], v[0:1], 0, s[18:19]
	s_nop 0
	v_addc_co_u32_e32 v5, vcc, 0, v1, vcc
	v_mov_b32_e32 v214, v8
	v_mov_b32_e32 v215, v9
	v_mov_b32_dpp v8, v10 row_ror:8 row_mask:0xf bank_mask:0xc
	v_mov_b32_dpp v9, v11 row_ror:8 row_mask:0xf bank_mask:0xc
	v_mov_b32_dpp v10, v214 row_ror:8 row_mask:0xf bank_mask:0x3
	v_mov_b32_dpp v11, v215 row_ror:8 row_mask:0xf bank_mask:0x3
	v_lshl_add_u64 v[216:217], v[4:5], 0, v[212:213]
	global_store_dwordx2 v[4:5], v[8:9], off
	global_store_dwordx2 v[216:217], v[10:11], off
	v_mov_b32_e32 v8, v65
	v_mov_b32_e32 v9, v65
	v_cvt_scalef32_pk_fp8_f32 v8, v112, v113, s14
	v_cvt_scalef32_pk_fp8_f32 v9, v108, v109, s14
	v_cvt_scalef32_pk_fp8_f32 v8, v114, v115, s14 op_sel:[0,0,0,1]
	v_cvt_scalef32_pk_fp8_f32 v9, v110, v111, s14 op_sel:[0,0,0,1]
	v_mov_b32_e32 v10, v65
	v_mov_b32_e32 v11, v65
	v_cvt_scalef32_pk_fp8_f32 v10, v104, v105, s14
	v_cvt_scalef32_pk_fp8_f32 v11, v100, v101, s14
	v_cvt_scalef32_pk_fp8_f32 v10, v106, v107, s14 op_sel:[0,0,0,1]
	v_cvt_scalef32_pk_fp8_f32 v11, v102, v103, s14 op_sel:[0,0,0,1]
	v_add_co_u32_e32 v4, vcc, s56, v0
	v_lshl_add_u64 v[2:3], v[0:1], 0, s[20:21]
	s_nop 0
	v_addc_co_u32_e32 v5, vcc, 0, v1, vcc
	v_mov_b32_e32 v214, v8
	v_mov_b32_e32 v215, v9
	v_mov_b32_dpp v8, v10 row_ror:8 row_mask:0xf bank_mask:0xc
	v_mov_b32_dpp v9, v11 row_ror:8 row_mask:0xf bank_mask:0xc
	v_mov_b32_dpp v10, v214 row_ror:8 row_mask:0xf bank_mask:0x3
	v_mov_b32_dpp v11, v215 row_ror:8 row_mask:0xf bank_mask:0x3
	v_lshl_add_u64 v[216:217], v[4:5], 0, v[212:213]
	global_store_dwordx2 v[4:5], v[8:9], off
	global_store_dwordx2 v[216:217], v[10:11], off
	v_mov_b32_e32 v8, v65
	v_mov_b32_e32 v9, v65
	v_cvt_scalef32_pk_fp8_f32 v8, v80, v81, s14
	v_cvt_scalef32_pk_fp8_f32 v9, v76, v77, s14
	v_cvt_scalef32_pk_fp8_f32 v8, v82, v83, s14 op_sel:[0,0,0,1]
	v_cvt_scalef32_pk_fp8_f32 v9, v78, v79, s14 op_sel:[0,0,0,1]
	v_mov_b32_e32 v10, v65
	v_mov_b32_e32 v11, v65
	v_cvt_scalef32_pk_fp8_f32 v10, v72, v73, s14
	v_cvt_scalef32_pk_fp8_f32 v11, v68, v69, s14
	v_lshl_add_u64 v[2:3], v[0:1], 0, s[22:23]
	v_cvt_scalef32_pk_fp8_f32 v10, v74, v75, s14 op_sel:[0,0,0,1]
	v_cvt_scalef32_pk_fp8_f32 v11, v70, v71, s14 op_sel:[0,0,0,1]
	v_add_co_u32_e32 v0, vcc, s57, v0
	s_mov_b64 s[8:9], -1
	s_mov_b32 s64, 1
	s_nop 0
	v_addc_co_u32_e32 v1, vcc, 0, v1, vcc
	s_andn2_b64 vcc, exec, s[24:25]
	v_mov_b32_e32 v214, v8
	v_mov_b32_e32 v215, v9
	v_mov_b32_dpp v8, v10 row_ror:8 row_mask:0xf bank_mask:0xc
	v_mov_b32_dpp v9, v11 row_ror:8 row_mask:0xf bank_mask:0xc
	v_mov_b32_dpp v10, v214 row_ror:8 row_mask:0xf bank_mask:0x3
	v_mov_b32_dpp v11, v215 row_ror:8 row_mask:0xf bank_mask:0x3
	v_lshl_add_u64 v[216:217], v[0:1], 0, v[212:213]
	global_store_dwordx2 v[0:1], v[8:9], off
	global_store_dwordx2 v[216:217], v[10:11], off
	s_cbranch_vccnz .LBB0_954
	s_andn2_b64 vcc, exec, s[10:11]
	s_cbranch_vccnz .LBB0_953
	s_barrier
	s_branch .LBB0_953
